# phase-0 gate/up weight conversion partly moved into the idle half-rounds of GEMM phases 1/5/7 (item ranges 10528/14528/18528), plus attention DMA placement
# speedup vs baseline: 1.0189x; 1.0050x over previous
.LBB0_20:
	s_lshr_b32 s89, s77, 6
	s_load_dwordx16 s[8:23], s[0:1], 0x40
	s_cmp_lt_i32 s28, 1
	s_cselect_b64 s[0:1], -1, 0
	s_cmp_gt_i32 s29, 0
	s_cselect_b64 s[2:3], -1, 0
	s_and_b64 s[2:3], s[0:1], s[2:3]
	s_andn2_b64 vcc, exec, s[2:3]
	v_and_b32_e32 v227, 63, v226
	s_cbranch_vccnz .LBB0_42
	s_mov_b32 s96, 0
	s_mov_b32 s97, 0x2920
	s_lshl_b32 s0, s76, 3
	s_add_i32 s4, s0, s89
.Lp0_entry:
	s_lshl_b32 s30, s33, 3
	s_cmp_ge_i32 s4, s97
	s_cbranch_scc1 .LBB0_30
	s_mul_hi_i32 s1, s4, 0x2e8ba2e9
	s_lshl_b32 s0, s89, 14
	s_lshr_b32 s5, s1, 31
	s_ashr_i32 s1, s1, 9
	s_add_i32 s0, s0, 0
	s_add_i32 s1, s1, s5
	s_bitcmp0_b32 s1, 0
	s_waitcnt lgkmcnt(0)
	s_cselect_b32 s5, s41, s43
	s_cselect_b32 s26, s40, s42
	s_ashr_i32 s27, s1, 1
	s_mul_hi_i32 s31, s27, 0x2c00000
	s_mul_i32 s27, s27, 0x2c00000
	s_add_u32 s34, s26, s27
	s_mulk_i32 s1, 0xb00
	s_addc_u32 s35, s5, s31
	s_sub_i32 s1, s4, s1
	s_bfe_u32 s5, s1, 0x5001a
	s_add_i32 s5, s1, s5
	s_sext_i32_i16 s26, s5
	s_and_b32 s5, s5, 0xffe0
	v_lshrrev_b32_e32 v0, 2, v226
	s_sub_i32 s1, s1, s5
	v_and_b32_e32 v128, 12, v0
	v_lshlrev_b32_e32 v0, 2, v226
	s_sext_i32_i16 s1, s1
	v_and_b32_e32 v130, 60, v0
	v_lshl_or_b32 v0, s1, 6, v128
	v_mul_i32_i24_e32 v0, 0x5800, v0
	v_ashrrev_i32_e32 v1, 31, v0
	s_lshl_b32 s1, s26, 1
	v_lshl_add_u64 v[0:1], s[34:35], 0, v[0:1]
	s_and_b32 s34, s1, 0xffffffc0
	s_ashr_i32 s35, s34, 31
	v_mov_b32_e32 v133, 0
	v_lshl_add_u64 v[0:1], s[34:35], 2, v[0:1]
	v_lshlrev_b32_e32 v132, 2, v130
	v_lshl_add_u64 v[8:9], v[0:1], 0, v[132:133]
	s_movk_i32 s5, 0x5000
	v_add_co_u32_e32 v10, vcc, s5, v8
	s_mov_b32 s31, 0xb000
	s_nop 0
	v_addc_co_u32_e32 v11, vcc, 0, v9, vcc
	global_load_dwordx4 v[0:3], v[8:9], off nt
	global_load_dwordx4 v[4:7], v[10:11], off offset:2048 nt
	v_add_co_u32_e32 v10, vcc, s31, v8
	s_mov_b32 s54, 0x10000
	s_nop 0
	v_addc_co_u32_e32 v11, vcc, 0, v9, vcc
	v_add_co_u32_e32 v12, vcc, s54, v8
	s_mov_b32 s55, 0x58000
	s_nop 0
	v_addc_co_u32_e32 v13, vcc, 0, v9, vcc
	v_add_co_u32_e32 v16, vcc, s55, v8
	s_mov_b32 s56, 0x5d000
	s_nop 0
	v_addc_co_u32_e32 v17, vcc, 0, v9, vcc
	v_add_co_u32_e32 v20, vcc, s56, v8
	s_mov_b32 s57, 0x63000
	s_nop 0
	v_addc_co_u32_e32 v21, vcc, 0, v9, vcc
	v_add_co_u32_e32 v24, vcc, s57, v8
	s_mov_b32 s58, 0x68000
	s_nop 0
	v_addc_co_u32_e32 v25, vcc, 0, v9, vcc
	v_add_co_u32_e32 v28, vcc, s58, v8
	s_mov_b32 s59, 0xb0000
	s_nop 0
	v_addc_co_u32_e32 v29, vcc, 0, v9, vcc
	v_add_co_u32_e32 v32, vcc, s59, v8
	s_mov_b32 s60, 0xb5000
	s_nop 0
	v_addc_co_u32_e32 v33, vcc, 0, v9, vcc
	v_add_co_u32_e32 v34, vcc, s60, v8
	s_mov_b32 s61, 0xbb000
	s_nop 0
	v_addc_co_u32_e32 v35, vcc, 0, v9, vcc
	v_add_co_u32_e32 v40, vcc, s61, v8
	s_mov_b32 s62, 0xc0000
	s_nop 0
	v_addc_co_u32_e32 v41, vcc, 0, v9, vcc
	v_add_co_u32_e32 v42, vcc, s62, v8
	s_mov_b32 s63, 0x108000
	s_nop 0
	v_addc_co_u32_e32 v43, vcc, 0, v9, vcc
	v_add_co_u32_e32 v48, vcc, s63, v8
	s_mov_b32 s1, 0x10d000
	s_nop 0
	v_addc_co_u32_e32 v49, vcc, 0, v9, vcc
	v_add_co_u32_e32 v50, vcc, s1, v8
	s_mov_b32 s1, 0x113000
	s_nop 0
	v_addc_co_u32_e32 v51, vcc, 0, v9, vcc
	v_add_co_u32_e32 v52, vcc, s1, v8
	s_mov_b32 s1, 0x118000
	s_nop 0
	v_addc_co_u32_e32 v53, vcc, 0, v9, vcc
	v_add_co_u32_e32 v54, vcc, s1, v8
	v_lshrrev_b32_e32 v129, 3, v227
	s_nop 0
	v_addc_co_u32_e32 v55, vcc, 0, v9, vcc
	global_load_dwordx4 v[8:11], v[10:11], off nt
	s_nop 0
	global_load_dwordx4 v[12:15], v[12:13], off offset:2048 nt
	s_nop 0
	global_load_dwordx4 v[16:19], v[16:17], off nt
	s_nop 0
	global_load_dwordx4 v[20:23], v[20:21], off offset:2048 nt
	s_nop 0
	global_load_dwordx4 v[24:27], v[24:25], off nt
	s_nop 0
	global_load_dwordx4 v[28:31], v[28:29], off offset:2048 nt
	s_nop 0
	global_load_dwordx4 v[36:39], v[32:33], off nt
	global_load_dwordx4 v[44:47], v[34:35], off offset:2048 nt
	global_load_dwordx4 v[56:59], v[40:41], off nt
	global_load_dwordx4 v[68:71], v[42:43], off offset:2048 nt
	global_load_dwordx4 v[80:83], v[48:49], off nt
	global_load_dwordx4 v[84:87], v[50:51], off offset:2048 nt
	global_load_dwordx4 v[96:99], v[52:53], off nt
	global_load_dwordx4 v[108:111], v[54:55], off offset:2048 nt
	v_and_b32_e32 v32, 7, v226
	v_lshl_add_u32 v33, v128, 1, s0
	v_mul_u32_u24_e32 v34, 0x90, v130
	v_lshl_add_u32 v35, v32, 4, s0
	v_lshlrev_b32_e32 v32, 3, v32
	v_mul_u32_u24_e32 v40, 0x90, v129
	v_or_b32_e32 v131, 8, v129
	v_or_b32_e32 v134, 16, v129
	v_or_b32_e32 v135, 24, v129
	v_or_b32_e32 v136, 32, v129
	v_or_b32_e32 v137, 40, v129
	v_or_b32_e32 v138, 48, v129
	v_or_b32_e32 v139, 56, v129
	v_lshlrev_b32_e32 v132, 1, v32
	s_lshl_b32 s64, s33, 4
	v_add_u32_e32 v140, v33, v34
	v_lshlrev_b32_e32 v141, 2, v128
	v_add_u32_e32 v142, v35, v40
	s_mov_b32 s65, s4
	s_branch .LBB0_25
.LBB0_23:
	s_lshr_b32 s0, s67, 31
	s_ashr_i32 s52, s67, 9
	s_add_i32 s52, s52, s0
	s_mul_i32 s0, s52, 0xb00
	s_sub_i32 s0, s66, s0
	s_bfe_u32 s1, s0, 0x5001a
	s_add_i32 s1, s0, s1
	s_sext_i32_i16 s53, s1
	s_and_b32 s1, s1, 0xffe0
	s_sub_i32 s0, s0, s1
	s_ashr_i32 s1, s52, 2
	s_and_b32 s26, s52, 2
	s_mul_i32 s1, s1, 3
	s_add_i32 s1, s1, s26
	s_lshl_b32 s34, s1, 1
	s_sext_i32_i16 s0, s0
	s_ashr_i32 s35, s34, 31
	s_add_i32 s65, s66, s30
	s_ashr_i32 s67, s52, 1
	s_lshl_b32 s0, s0, 6
	s_lshl_b64 s[34:35], s[34:35], 13
	s_add_u32 s26, s38, s34
	s_addc_u32 s27, s39, s35
	s_ashr_i32 s1, s0, 31
	s_lshl_b64 s[34:35], s[0:1], 2
	s_add_u32 s34, s26, s34
	s_addc_u32 s35, s27, s35
	global_load_dwordx4 v[144:147], v141, s[34:35]
	s_ashr_i32 s26, s53, 5
	s_mul_hi_i32 s66, s67, 0x2c00000
	s_mul_i32 s67, s67, 0x2c00000
	s_lshl_b32 s27, s26, 6
	s_waitcnt vmcnt(0)
	v_mul_f32_e32 v143, v32, v144
	v_mul_f32_e32 v148, v40, v145
	v_cvt_pk_bf16_f32 v148, v143, v148
	v_mul_f32_e32 v143, v48, v146
	v_mul_f32_e32 v149, v52, v147
	v_cvt_pk_bf16_f32 v149, v143, v149
	ds_write_b64 v140, v[148:149]
	v_mul_f32_e32 v143, v33, v144
	v_mul_f32_e32 v148, v41, v145
	v_cvt_pk_bf16_f32 v148, v143, v148
	v_mul_f32_e32 v143, v49, v146
	v_mul_f32_e32 v149, v53, v147
	v_cvt_pk_bf16_f32 v149, v143, v149
	ds_write_b64 v140, v[148:149] offset:144
	v_mul_f32_e32 v143, v34, v144
	v_mul_f32_e32 v148, v42, v145
	v_cvt_pk_bf16_f32 v148, v143, v148
	v_mul_f32_e32 v143, v50, v146
	v_mul_f32_e32 v149, v54, v147
	v_cvt_pk_bf16_f32 v149, v143, v149
	v_mul_f32_e32 v143, v35, v144
	v_mul_f32_e32 v144, v43, v145
	v_mul_f32_e32 v145, v55, v147
	ds_write_b64 v140, v[148:149] offset:288
	v_cvt_pk_bf16_f32 v144, v143, v144
	v_mul_f32_e32 v143, v51, v146
	v_cvt_pk_bf16_f32 v145, v143, v145
	ds_write_b64 v140, v[144:145] offset:432
	global_load_dwordx4 v[144:147], v141, s[34:35] offset:64
	s_waitcnt vmcnt(0)
	v_mul_f32_e32 v143, v60, v144
	v_mul_f32_e32 v148, v64, v145
	v_cvt_pk_bf16_f32 v148, v143, v148
	v_mul_f32_e32 v143, v72, v146
	v_mul_f32_e32 v149, v76, v147
	v_cvt_pk_bf16_f32 v149, v143, v149
	ds_write_b64 v140, v[148:149] offset:32
	v_mul_f32_e32 v143, v61, v144
	v_mul_f32_e32 v148, v65, v145
	v_cvt_pk_bf16_f32 v148, v143, v148
	v_mul_f32_e32 v143, v73, v146
	v_mul_f32_e32 v149, v77, v147
	v_cvt_pk_bf16_f32 v149, v143, v149
	ds_write_b64 v140, v[148:149] offset:176
	v_mul_f32_e32 v143, v62, v144
	v_mul_f32_e32 v148, v66, v145
	v_cvt_pk_bf16_f32 v148, v143, v148
	v_mul_f32_e32 v143, v74, v146
	v_mul_f32_e32 v149, v78, v147
	v_cvt_pk_bf16_f32 v149, v143, v149
	v_mul_f32_e32 v143, v63, v144
	v_mul_f32_e32 v144, v67, v145
	v_mul_f32_e32 v145, v79, v147
	ds_write_b64 v140, v[148:149] offset:320
	v_cvt_pk_bf16_f32 v144, v143, v144
	v_mul_f32_e32 v143, v75, v146
	v_cvt_pk_bf16_f32 v145, v143, v145
	ds_write_b64 v140, v[144:145] offset:464
	global_load_dwordx4 v[144:147], v141, s[34:35] offset:128
	s_waitcnt vmcnt(0)
	v_mul_f32_e32 v143, v88, v144
	v_mul_f32_e32 v148, v92, v145
	v_cvt_pk_bf16_f32 v148, v143, v148
	v_mul_f32_e32 v143, v100, v146
	v_mul_f32_e32 v149, v104, v147
	v_cvt_pk_bf16_f32 v149, v143, v149
	ds_write_b64 v140, v[148:149] offset:64
	v_mul_f32_e32 v143, v89, v144
	v_mul_f32_e32 v148, v93, v145
	v_cvt_pk_bf16_f32 v148, v143, v148
	v_mul_f32_e32 v143, v101, v146
	v_mul_f32_e32 v149, v105, v147
	v_cvt_pk_bf16_f32 v149, v143, v149
	ds_write_b64 v140, v[148:149] offset:208
	v_mul_f32_e32 v143, v90, v144
	v_mul_f32_e32 v148, v94, v145
	v_cvt_pk_bf16_f32 v148, v143, v148
	v_mul_f32_e32 v143, v102, v146
	v_mul_f32_e32 v149, v106, v147
	v_cvt_pk_bf16_f32 v149, v143, v149
	v_mul_f32_e32 v143, v91, v144
	v_mul_f32_e32 v144, v95, v145
	v_mul_f32_e32 v145, v107, v147
	ds_write_b64 v140, v[148:149] offset:352
	v_cvt_pk_bf16_f32 v144, v143, v144
	v_mul_f32_e32 v143, v103, v146
	v_cvt_pk_bf16_f32 v145, v143, v145
	ds_write_b64 v140, v[144:145] offset:496
	global_load_dwordx4 v[144:147], v141, s[34:35] offset:192
	s_add_u32 s34, s24, s67
	s_addc_u32 s35, s25, s66
	s_lshl_b32 s52, s52, 7
	s_lshl_b32 s26, s26, 7
	s_and_b32 s27, s27, 64
	s_and_b32 s52, s52, 0x80
	s_and_b32 s26, s26, 0xffffff00
	s_or_b32 s27, s27, s52
	s_or_b32 s26, s27, s26
	s_lshl_b64 s[0:1], s[0:1], 1
	s_add_u32 s0, s34, s0
	v_or_b32_e32 v150, s26, v129
	s_addc_u32 s1, s35, s1
	v_ashrrev_i32_e32 v151, 31, v150
	v_lshlrev_b64 v[150:151], 12, v[150:151]
	s_cmp_ge_i32 s65, s97
	s_cselect_b64 s[34:35], -1, 0
	s_waitcnt vmcnt(0)
	v_mul_f32_e32 v143, v112, v144
	v_mul_f32_e32 v148, v116, v145
	v_cvt_pk_bf16_f32 v148, v143, v148
	v_mul_f32_e32 v143, v120, v146
	v_mul_f32_e32 v149, v124, v147
	v_cvt_pk_bf16_f32 v149, v143, v149
	ds_write_b64 v140, v[148:149] offset:96
	v_mul_f32_e32 v143, v113, v144
	v_mul_f32_e32 v148, v117, v145
	v_cvt_pk_bf16_f32 v148, v143, v148
	v_mul_f32_e32 v143, v121, v146
	v_mul_f32_e32 v149, v125, v147
	v_cvt_pk_bf16_f32 v149, v143, v149
	ds_write_b64 v140, v[148:149] offset:240
	v_mul_f32_e32 v143, v114, v144
	v_mul_f32_e32 v148, v118, v145
	v_cvt_pk_bf16_f32 v148, v143, v148
	v_mul_f32_e32 v143, v122, v146
	v_mul_f32_e32 v149, v126, v147
	v_cvt_pk_bf16_f32 v149, v143, v149
	v_mul_f32_e32 v143, v115, v144
	v_mul_f32_e32 v144, v119, v145
	v_mul_f32_e32 v145, v127, v147
	ds_write_b64 v140, v[148:149] offset:384
	v_cvt_pk_bf16_f32 v144, v143, v144
	v_mul_f32_e32 v143, v123, v146
	v_cvt_pk_bf16_f32 v145, v143, v145
	ds_write_b64 v140, v[144:145] offset:528
	s_waitcnt lgkmcnt(0)
	ds_read_b128 v[144:147], v142
	v_lshl_add_u64 v[148:149], s[0:1], 0, v[132:133]
	v_lshl_add_u64 v[150:151], v[148:149], 0, v[150:151]
	s_waitcnt lgkmcnt(0)
	global_store_dwordx4 v[150:151], v[144:147], off
	ds_read_b128 v[144:147], v142 offset:1152
	v_or_b32_e32 v150, s26, v131
	v_ashrrev_i32_e32 v151, 31, v150
	v_lshlrev_b64 v[150:151], 12, v[150:151]
	v_lshl_add_u64 v[150:151], v[148:149], 0, v[150:151]
	s_waitcnt lgkmcnt(0)
	global_store_dwordx4 v[150:151], v[144:147], off
	ds_read_b128 v[144:147], v142 offset:2304
	v_or_b32_e32 v150, s26, v134
	v_ashrrev_i32_e32 v151, 31, v150
	v_lshlrev_b64 v[150:151], 12, v[150:151]
	v_lshl_add_u64 v[150:151], v[148:149], 0, v[150:151]
	s_waitcnt lgkmcnt(0)
	global_store_dwordx4 v[150:151], v[144:147], off
	ds_read_b128 v[144:147], v142 offset:3456
	v_or_b32_e32 v150, s26, v135
	v_ashrrev_i32_e32 v151, 31, v150
	v_lshlrev_b64 v[150:151], 12, v[150:151]
	v_lshl_add_u64 v[150:151], v[148:149], 0, v[150:151]
	s_waitcnt lgkmcnt(0)
	global_store_dwordx4 v[150:151], v[144:147], off
	ds_read_b128 v[144:147], v142 offset:4608
	v_or_b32_e32 v150, s26, v136
	v_ashrrev_i32_e32 v151, 31, v150
	v_lshlrev_b64 v[150:151], 12, v[150:151]
	v_lshl_add_u64 v[150:151], v[148:149], 0, v[150:151]
	s_waitcnt lgkmcnt(0)
	global_store_dwordx4 v[150:151], v[144:147], off
	ds_read_b128 v[144:147], v142 offset:5760
	v_or_b32_e32 v150, s26, v137
	v_ashrrev_i32_e32 v151, 31, v150
	v_lshlrev_b64 v[150:151], 12, v[150:151]
	v_lshl_add_u64 v[150:151], v[148:149], 0, v[150:151]
	s_waitcnt lgkmcnt(0)
	global_store_dwordx4 v[150:151], v[144:147], off
	ds_read_b128 v[144:147], v142 offset:6912
	v_or_b32_e32 v150, s26, v138
	v_ashrrev_i32_e32 v151, 31, v150
	v_lshlrev_b64 v[150:151], 12, v[150:151]
	v_lshl_add_u64 v[150:151], v[148:149], 0, v[150:151]
	s_waitcnt lgkmcnt(0)
	global_store_dwordx4 v[150:151], v[144:147], off
	ds_read_b128 v[144:147], v142 offset:8064
	v_or_b32_e32 v150, s26, v139
	v_ashrrev_i32_e32 v151, 31, v150
	v_lshlrev_b64 v[150:151], 12, v[150:151]
	v_lshl_add_u64 v[148:149], v[148:149], 0, v[150:151]
	s_waitcnt lgkmcnt(0)
	global_store_dwordx4 v[148:149], v[144:147], off
	s_waitcnt lgkmcnt(0)

.LBB0_25:
	s_add_i32 s66, s65, s30
	s_cmp_lt_i32 s66, s97
	s_cselect_b64 s[0:1], -1, 0
	s_cmp_ge_i32 s66, s97
	s_mul_hi_i32 s67, s66, 0x2e8ba2e9
	s_cbranch_scc1 .LBB0_27
	s_lshr_b32 s26, s67, 31
	s_ashr_i32 s27, s67, 9
	s_add_i32 s26, s27, s26
	s_mul_i32 s27, s26, 0xb00
	s_sub_i32 s27, s66, s27
	s_sext_i32_i16 s34, s27
	s_bfe_u32 s34, s34, 0x5001a
	s_add_i32 s34, s27, s34
	s_sext_i32_i16 s52, s34
	s_and_b32 s34, s34, 0xffe0
	s_sub_i32 s27, s27, s34
	s_bitcmp0_b32 s26, 0
	s_sext_i32_i16 s27, s27
	s_cselect_b32 s35, s41, s43
	s_cselect_b32 s34, s40, s42
	s_ashr_i32 s26, s26, 1
	s_mul_hi_i32 s53, s26, 0x2c00000
	s_mul_i32 s26, s26, 0x2c00000
	v_lshl_or_b32 v32, s27, 6, v128
	s_add_u32 s34, s34, s26
	v_mul_i32_i24_e32 v32, 0x5800, v32
	s_addc_u32 s35, s35, s53
	v_ashrrev_i32_e32 v33, 31, v32
	s_lshl_b32 s26, s52, 1
	v_lshl_add_u64 v[32:33], s[34:35], 0, v[32:33]
	s_and_b32 s34, s26, 0xffffffc0
	s_ashr_i32 s35, s34, 31
	v_lshl_add_u64 v[32:33], s[34:35], 2, v[32:33]
	v_lshlrev_b32_e32 v34, 2, v130
	v_mov_b32_e32 v35, v133
	v_lshl_add_u64 v[120:121], v[32:33], 0, v[34:35]
	v_add_co_u32_e32 v40, vcc, s5, v120
	s_nop 1
	v_addc_co_u32_e32 v41, vcc, 0, v121, vcc
	v_add_co_u32_e32 v48, vcc, s31, v120
	global_load_dwordx4 v[32:35], v[120:121], off nt
	s_nop 0
	global_load_dwordx4 v[40:43], v[40:41], off offset:2048 nt
	v_addc_co_u32_e32 v49, vcc, 0, v121, vcc
	v_add_co_u32_e32 v52, vcc, s54, v120
	s_nop 1
	v_addc_co_u32_e32 v53, vcc, 0, v121, vcc
	v_add_co_u32_e32 v60, vcc, s55, v120
	global_load_dwordx4 v[48:51], v[48:49], off nt
	s_nop 0
	global_load_dwordx4 v[52:55], v[52:53], off offset:2048 nt
	v_addc_co_u32_e32 v61, vcc, 0, v121, vcc
	v_add_co_u32_e32 v64, vcc, s56, v120
	s_nop 1
	v_addc_co_u32_e32 v65, vcc, 0, v121, vcc
	v_add_co_u32_e32 v72, vcc, s57, v120
	global_load_dwordx4 v[60:63], v[60:61], off nt
	s_nop 0
	global_load_dwordx4 v[64:67], v[64:65], off offset:2048 nt
	v_addc_co_u32_e32 v73, vcc, 0, v121, vcc
	v_add_co_u32_e32 v76, vcc, s58, v120
	s_nop 1
	v_addc_co_u32_e32 v77, vcc, 0, v121, vcc
	v_add_co_u32_e32 v88, vcc, s59, v120
	global_load_dwordx4 v[72:75], v[72:73], off nt
	s_nop 0
	global_load_dwordx4 v[76:79], v[76:77], off offset:2048 nt
	v_addc_co_u32_e32 v89, vcc, 0, v121, vcc
	v_add_co_u32_e32 v92, vcc, s60, v120
	s_nop 1
	v_addc_co_u32_e32 v93, vcc, 0, v121, vcc
	v_add_co_u32_e32 v100, vcc, s61, v120
	global_load_dwordx4 v[88:91], v[88:89], off nt
	s_nop 0
	global_load_dwordx4 v[92:95], v[92:93], off offset:2048 nt
	v_addc_co_u32_e32 v101, vcc, 0, v121, vcc
	v_add_co_u32_e32 v104, vcc, s62, v120
	s_nop 1
	v_addc_co_u32_e32 v105, vcc, 0, v121, vcc
	v_add_co_u32_e32 v112, vcc, 0x108000, v120
	global_load_dwordx4 v[100:103], v[100:101], off nt
	s_nop 0
	global_load_dwordx4 v[104:107], v[104:105], off offset:2048 nt
	v_addc_co_u32_e32 v113, vcc, 0, v121, vcc
	v_add_co_u32_e32 v116, vcc, 0x10d000, v120
	s_nop 1
	v_addc_co_u32_e32 v117, vcc, 0, v121, vcc
	v_add_co_u32_e32 v122, vcc, 0x113000, v120
	global_load_dwordx4 v[112:115], v[112:113], off nt
	s_nop 0
	global_load_dwordx4 v[116:119], v[116:117], off offset:2048 nt
	v_addc_co_u32_e32 v123, vcc, 0, v121, vcc
	v_add_co_u32_e32 v124, vcc, 0x118000, v120
	s_nop 1
	v_addc_co_u32_e32 v125, vcc, 0, v121, vcc
	global_load_dwordx4 v[120:123], v[122:123], off nt
	s_nop 0
	global_load_dwordx4 v[124:127], v[124:125], off offset:2048 nt
.LBB0_27:
	s_mul_hi_i32 s26, s65, 0x2e8ba2e9
	s_lshr_b32 s27, s26, 31
	s_ashr_i32 s68, s26, 9
	s_add_i32 s68, s68, s27
	s_mul_i32 s26, s68, 0xb00
	s_sub_i32 s26, s65, s26
	s_bfe_u32 s27, s26, 0x5001a
	s_add_i32 s27, s26, s27
	s_sext_i32_i16 s69, s27
	s_and_b32 s27, s27, 0xffe0
	s_sub_i32 s26, s26, s27
	s_sext_i32_i16 s26, s26
	s_lshl_b32 s34, s26, 6
	s_ashr_i32 s26, s68, 2
	s_and_b32 s27, s68, 2
	s_mul_i32 s26, s26, 3
	s_add_i32 s26, s26, s27
	s_lshl_b32 s52, s26, 1
	s_ashr_i32 s53, s52, 31
	s_ashr_i32 s71, s68, 1
	s_lshl_b64 s[52:53], s[52:53], 13
	s_add_u32 s26, s38, s52
	s_addc_u32 s27, s39, s53
	s_ashr_i32 s35, s34, 31
	s_lshl_b64 s[52:53], s[34:35], 2
	s_add_u32 s52, s26, s52
	s_addc_u32 s53, s27, s53
	global_load_dwordx4 v[144:147], v141, s[52:53]
	s_ashr_i32 s26, s69, 5
	s_mul_hi_i32 s70, s71, 0x2c00000
	s_mul_i32 s71, s71, 0x2c00000
	s_lshl_b32 s27, s26, 6
	s_waitcnt vmcnt(0)
	v_mul_f32_e32 v143, v0, v144
	v_mul_f32_e32 v148, v4, v145
	v_cvt_pk_bf16_f32 v148, v143, v148
	v_mul_f32_e32 v143, v8, v146
	v_mul_f32_e32 v149, v12, v147
	v_cvt_pk_bf16_f32 v149, v143, v149
	ds_write_b64 v140, v[148:149]
	v_mul_f32_e32 v143, v1, v144
	v_mul_f32_e32 v148, v5, v145
	v_cvt_pk_bf16_f32 v148, v143, v148
	v_mul_f32_e32 v143, v9, v146
	v_mul_f32_e32 v149, v13, v147
	v_cvt_pk_bf16_f32 v149, v143, v149
	ds_write_b64 v140, v[148:149] offset:144
	v_mul_f32_e32 v143, v2, v144
	v_mul_f32_e32 v148, v6, v145
	v_cvt_pk_bf16_f32 v148, v143, v148
	v_mul_f32_e32 v143, v10, v146
	v_mul_f32_e32 v149, v14, v147
	v_cvt_pk_bf16_f32 v149, v143, v149
	v_mul_f32_e32 v143, v3, v144
	v_mul_f32_e32 v144, v7, v145
	v_mul_f32_e32 v145, v15, v147
	ds_write_b64 v140, v[148:149] offset:288
	v_cvt_pk_bf16_f32 v144, v143, v144
	v_mul_f32_e32 v143, v11, v146
	v_cvt_pk_bf16_f32 v145, v143, v145
	ds_write_b64 v140, v[144:145] offset:432
	global_load_dwordx4 v[144:147], v141, s[52:53] offset:64
	s_waitcnt vmcnt(0)
	v_mul_f32_e32 v143, v16, v144
	v_mul_f32_e32 v148, v20, v145
	v_cvt_pk_bf16_f32 v148, v143, v148
	v_mul_f32_e32 v143, v24, v146
	v_mul_f32_e32 v149, v28, v147
	v_cvt_pk_bf16_f32 v149, v143, v149
	ds_write_b64 v140, v[148:149] offset:32
	v_mul_f32_e32 v143, v17, v144
	v_mul_f32_e32 v148, v21, v145
	v_cvt_pk_bf16_f32 v148, v143, v148
	v_mul_f32_e32 v143, v25, v146
	v_mul_f32_e32 v149, v29, v147
	v_cvt_pk_bf16_f32 v149, v143, v149
	ds_write_b64 v140, v[148:149] offset:176
	v_mul_f32_e32 v143, v18, v144
	v_mul_f32_e32 v148, v22, v145
	v_cvt_pk_bf16_f32 v148, v143, v148
	v_mul_f32_e32 v143, v26, v146
	v_mul_f32_e32 v149, v30, v147
	v_cvt_pk_bf16_f32 v149, v143, v149
	v_mul_f32_e32 v143, v19, v144
	v_mul_f32_e32 v144, v23, v145
	v_mul_f32_e32 v145, v31, v147
	ds_write_b64 v140, v[148:149] offset:320
	v_cvt_pk_bf16_f32 v144, v143, v144
	v_mul_f32_e32 v143, v27, v146
	v_cvt_pk_bf16_f32 v145, v143, v145
	ds_write_b64 v140, v[144:145] offset:464
	global_load_dwordx4 v[144:147], v141, s[52:53] offset:128
	s_waitcnt vmcnt(0)
	v_mul_f32_e32 v143, v36, v144
	v_mul_f32_e32 v148, v44, v145
	v_cvt_pk_bf16_f32 v148, v143, v148
	v_mul_f32_e32 v143, v56, v146
	v_mul_f32_e32 v149, v68, v147
	v_cvt_pk_bf16_f32 v149, v143, v149
	ds_write_b64 v140, v[148:149] offset:64
	v_mul_f32_e32 v143, v37, v144
	v_mul_f32_e32 v148, v45, v145
	v_cvt_pk_bf16_f32 v148, v143, v148
	v_mul_f32_e32 v143, v57, v146
	v_mul_f32_e32 v149, v69, v147
	v_cvt_pk_bf16_f32 v149, v143, v149
	ds_write_b64 v140, v[148:149] offset:208
	v_mul_f32_e32 v143, v38, v144
	v_mul_f32_e32 v148, v46, v145
	v_cvt_pk_bf16_f32 v148, v143, v148
	v_mul_f32_e32 v143, v58, v146
	v_mul_f32_e32 v149, v70, v147
	v_cvt_pk_bf16_f32 v149, v143, v149
	v_mul_f32_e32 v143, v39, v144
	v_mul_f32_e32 v144, v47, v145
	v_mul_f32_e32 v145, v71, v147
	ds_write_b64 v140, v[148:149] offset:352
	v_cvt_pk_bf16_f32 v144, v143, v144
	v_mul_f32_e32 v143, v59, v146
	v_cvt_pk_bf16_f32 v145, v143, v145
	ds_write_b64 v140, v[144:145] offset:496
	global_load_dwordx4 v[144:147], v141, s[52:53] offset:192
	s_add_u32 s52, s24, s71
	s_addc_u32 s53, s25, s70
	s_lshl_b32 s68, s68, 7
	s_lshl_b32 s26, s26, 7
	s_and_b32 s27, s27, 64
	s_and_b32 s68, s68, 0x80
	s_and_b32 s26, s26, 0xffffff00
	s_or_b32 s27, s27, s68
	s_or_b32 s26, s27, s26
	s_lshl_b64 s[34:35], s[34:35], 1
	s_add_u32 s34, s52, s34
	v_or_b32_e32 v150, s26, v129
	s_addc_u32 s35, s53, s35
	v_ashrrev_i32_e32 v151, 31, v150
	v_lshlrev_b64 v[150:151], 12, v[150:151]
	s_andn2_b64 vcc, exec, s[0:1]
	s_waitcnt vmcnt(0)
	v_mul_f32_e32 v143, v80, v144
	v_mul_f32_e32 v148, v84, v145
	v_cvt_pk_bf16_f32 v148, v143, v148
	v_mul_f32_e32 v143, v96, v146
	v_mul_f32_e32 v149, v108, v147
	v_cvt_pk_bf16_f32 v149, v143, v149
	ds_write_b64 v140, v[148:149] offset:96
	v_mul_f32_e32 v143, v81, v144
	v_mul_f32_e32 v148, v85, v145
	v_cvt_pk_bf16_f32 v148, v143, v148
	v_mul_f32_e32 v143, v97, v146
	v_mul_f32_e32 v149, v109, v147
	v_cvt_pk_bf16_f32 v149, v143, v149
	ds_write_b64 v140, v[148:149] offset:240
	v_mul_f32_e32 v143, v82, v144
	v_mul_f32_e32 v148, v86, v145
	v_cvt_pk_bf16_f32 v148, v143, v148
	v_mul_f32_e32 v143, v98, v146
	v_mul_f32_e32 v149, v110, v147
	v_cvt_pk_bf16_f32 v149, v143, v149
	v_mul_f32_e32 v143, v83, v144
	v_mul_f32_e32 v144, v87, v145
	v_mul_f32_e32 v145, v111, v147
	ds_write_b64 v140, v[148:149] offset:384
	v_cvt_pk_bf16_f32 v144, v143, v144
	v_mul_f32_e32 v143, v99, v146
	v_cvt_pk_bf16_f32 v145, v143, v145
	ds_write_b64 v140, v[144:145] offset:528
	s_waitcnt lgkmcnt(0)
	ds_read_b128 v[144:147], v142
	v_lshl_add_u64 v[148:149], s[34:35], 0, v[132:133]
	v_lshl_add_u64 v[150:151], v[148:149], 0, v[150:151]
	s_mov_b64 s[34:35], -1
	s_waitcnt lgkmcnt(0)
	global_store_dwordx4 v[150:151], v[144:147], off
	ds_read_b128 v[144:147], v142 offset:1152
	v_or_b32_e32 v150, s26, v131
	v_ashrrev_i32_e32 v151, 31, v150
	v_lshlrev_b64 v[150:151], 12, v[150:151]
	v_lshl_add_u64 v[150:151], v[148:149], 0, v[150:151]
	s_waitcnt lgkmcnt(0)
	global_store_dwordx4 v[150:151], v[144:147], off
	ds_read_b128 v[144:147], v142 offset:2304
	v_or_b32_e32 v150, s26, v134
	v_ashrrev_i32_e32 v151, 31, v150
	v_lshlrev_b64 v[150:151], 12, v[150:151]
	v_lshl_add_u64 v[150:151], v[148:149], 0, v[150:151]
	s_waitcnt lgkmcnt(0)
	global_store_dwordx4 v[150:151], v[144:147], off
	ds_read_b128 v[144:147], v142 offset:3456
	v_or_b32_e32 v150, s26, v135
	v_ashrrev_i32_e32 v151, 31, v150
	v_lshlrev_b64 v[150:151], 12, v[150:151]
	v_lshl_add_u64 v[150:151], v[148:149], 0, v[150:151]
	s_waitcnt lgkmcnt(0)
	global_store_dwordx4 v[150:151], v[144:147], off
	ds_read_b128 v[144:147], v142 offset:4608
	v_or_b32_e32 v150, s26, v136
	v_ashrrev_i32_e32 v151, 31, v150
	v_lshlrev_b64 v[150:151], 12, v[150:151]
	v_lshl_add_u64 v[150:151], v[148:149], 0, v[150:151]
	s_waitcnt lgkmcnt(0)
	global_store_dwordx4 v[150:151], v[144:147], off
	ds_read_b128 v[144:147], v142 offset:5760
	v_or_b32_e32 v150, s26, v137
	v_ashrrev_i32_e32 v151, 31, v150
	v_lshlrev_b64 v[150:151], 12, v[150:151]
	v_lshl_add_u64 v[150:151], v[148:149], 0, v[150:151]
	s_waitcnt lgkmcnt(0)
	global_store_dwordx4 v[150:151], v[144:147], off
	ds_read_b128 v[144:147], v142 offset:6912
	v_or_b32_e32 v150, s26, v138
	v_ashrrev_i32_e32 v151, 31, v150
	v_lshlrev_b64 v[150:151], 12, v[150:151]
	v_lshl_add_u64 v[150:151], v[148:149], 0, v[150:151]
	s_waitcnt lgkmcnt(0)
	global_store_dwordx4 v[150:151], v[144:147], off
	ds_read_b128 v[144:147], v142 offset:8064
	v_or_b32_e32 v150, s26, v139
	v_ashrrev_i32_e32 v151, 31, v150
	v_lshlrev_b64 v[150:151], 12, v[150:151]
	v_lshl_add_u64 v[148:149], v[148:149], 0, v[150:151]
	s_waitcnt lgkmcnt(0)
	global_store_dwordx4 v[148:149], v[144:147], off
	s_waitcnt lgkmcnt(0)
	s_cbranch_vccnz .LBB0_24
	s_add_i32 s0, s64, s65
	s_cmp_ge_i32 s0, s97
	s_cbranch_scc1 .LBB0_23
	s_mul_hi_i32 s1, s0, 0x2e8ba2e9
	s_lshr_b32 s26, s1, 31
	s_ashr_i32 s1, s1, 9
	s_add_i32 s1, s1, s26
	s_mul_i32 s26, s1, 0xb00
	s_sub_i32 s0, s0, s26
	s_bfe_u32 s26, s0, 0x5001a
	s_add_i32 s26, s0, s26
	s_sext_i32_i16 s27, s26
	s_and_b32 s26, s26, 0xffe0
	s_sub_i32 s0, s0, s26
	s_bitcmp0_b32 s1, 0
	s_sext_i32_i16 s26, s0
	s_cselect_b32 s34, s41, s43
	s_cselect_b32 s0, s40, s42
	s_ashr_i32 s1, s1, 1
	s_mul_hi_i32 s35, s1, 0x2c00000
	s_mul_i32 s1, s1, 0x2c00000
	v_lshl_or_b32 v0, s26, 6, v128
	s_add_u32 s0, s0, s1
	v_mul_i32_i24_e32 v0, 0x5800, v0
	s_addc_u32 s1, s34, s35
	v_ashrrev_i32_e32 v1, 31, v0
	v_lshl_add_u64 v[0:1], s[0:1], 0, v[0:1]
	s_lshl_b32 s0, s27, 1
	s_andn2_b32 s0, s0, 63
	s_ashr_i32 s1, s0, 31
	v_lshl_add_u64 v[0:1], s[0:1], 2, v[0:1]
	v_lshlrev_b32_e32 v2, 2, v130
	v_mov_b32_e32 v3, v133
	v_lshl_add_u64 v[96:97], v[0:1], 0, v[2:3]
	v_add_co_u32_e32 v4, vcc, s5, v96
	s_nop 1
	v_addc_co_u32_e32 v5, vcc, 0, v97, vcc
	v_add_co_u32_e32 v8, vcc, s31, v96
	global_load_dwordx4 v[0:3], v[96:97], off nt
	s_nop 0
	global_load_dwordx4 v[4:7], v[4:5], off offset:2048 nt
	v_addc_co_u32_e32 v9, vcc, 0, v97, vcc
	v_add_co_u32_e32 v12, vcc, s54, v96
	s_nop 1
	v_addc_co_u32_e32 v13, vcc, 0, v97, vcc
	v_add_co_u32_e32 v16, vcc, s55, v96
	global_load_dwordx4 v[8:11], v[8:9], off nt
	s_nop 0
	global_load_dwordx4 v[12:15], v[12:13], off offset:2048 nt
	v_addc_co_u32_e32 v17, vcc, 0, v97, vcc
	v_add_co_u32_e32 v20, vcc, s56, v96
	s_nop 1
	v_addc_co_u32_e32 v21, vcc, 0, v97, vcc
	v_add_co_u32_e32 v24, vcc, s57, v96
	global_load_dwordx4 v[16:19], v[16:17], off nt
	s_nop 0
	global_load_dwordx4 v[20:23], v[20:21], off offset:2048 nt
	v_addc_co_u32_e32 v25, vcc, 0, v97, vcc
	v_add_co_u32_e32 v28, vcc, s58, v96
	s_nop 1
	v_addc_co_u32_e32 v29, vcc, 0, v97, vcc
	v_add_co_u32_e32 v36, vcc, s59, v96
	global_load_dwordx4 v[24:27], v[24:25], off nt
	s_nop 0
	global_load_dwordx4 v[28:31], v[28:29], off offset:2048 nt
	v_addc_co_u32_e32 v37, vcc, 0, v97, vcc
	v_add_co_u32_e32 v44, vcc, s60, v96
	s_nop 1
	v_addc_co_u32_e32 v45, vcc, 0, v97, vcc
	v_add_co_u32_e32 v56, vcc, s61, v96
	global_load_dwordx4 v[36:39], v[36:37], off nt
	s_nop 0
	global_load_dwordx4 v[44:47], v[44:45], off offset:2048 nt
	v_addc_co_u32_e32 v57, vcc, 0, v97, vcc
	v_add_co_u32_e32 v68, vcc, s62, v96
	s_nop 1
	v_addc_co_u32_e32 v69, vcc, 0, v97, vcc
	v_add_co_u32_e32 v80, vcc, s63, v96
	global_load_dwordx4 v[56:59], v[56:57], off nt
	s_nop 0
	global_load_dwordx4 v[68:71], v[68:69], off offset:2048 nt
	v_addc_co_u32_e32 v81, vcc, 0, v97, vcc
	v_add_co_u32_e32 v84, vcc, 0x10d000, v96
	s_nop 1
	v_addc_co_u32_e32 v85, vcc, 0, v97, vcc
	v_add_co_u32_e32 v98, vcc, 0x113000, v96
	global_load_dwordx4 v[80:83], v[80:81], off nt
	s_nop 0
	global_load_dwordx4 v[84:87], v[84:85], off offset:2048 nt
	v_addc_co_u32_e32 v99, vcc, 0, v97, vcc
	v_add_co_u32_e32 v108, vcc, 0x118000, v96
	s_nop 1
	v_addc_co_u32_e32 v109, vcc, 0, v97, vcc
	global_load_dwordx4 v[96:99], v[98:99], off nt
	s_nop 0
	global_load_dwordx4 v[108:111], v[108:109], off offset:2048 nt
	s_branch .LBB0_23
.LBB0_30:
	s_cmp_eq_u32 s96, 0
	s_cbranch_scc1 .Lp0_normal
	s_cmp_eq_u32 s96, 1
	s_cbranch_scc1 .Lp0ret_1
	s_cmp_eq_u32 s96, 2
	s_cbranch_scc1 .Lp0ret_2
	s_branch .Lp0ret_3

.Lp0call_1:
	v_writelane_b32 v251, s0, 0
	v_writelane_b32 v251, s1, 1
	v_writelane_b32 v251, s4, 2
	v_writelane_b32 v251, s5, 3
	v_writelane_b32 v251, s26, 4
	v_writelane_b32 v251, s27, 5
	v_writelane_b32 v251, s30, 6
	v_writelane_b32 v251, s31, 7
	v_writelane_b32 v251, s34, 8
	v_writelane_b32 v251, s35, 9
	v_writelane_b32 v251, s52, 10
	v_writelane_b32 v251, s53, 11
	v_writelane_b32 v251, s54, 12
	v_writelane_b32 v251, s55, 13
	v_writelane_b32 v251, s56, 14
	v_writelane_b32 v251, s57, 15
	v_writelane_b32 v251, s58, 16
	v_writelane_b32 v251, s59, 17
	v_writelane_b32 v251, s60, 18
	v_writelane_b32 v251, s61, 19
	v_writelane_b32 v251, s62, 20
	v_writelane_b32 v251, s63, 21
	v_writelane_b32 v251, s64, 22
	v_writelane_b32 v251, s65, 23
	v_writelane_b32 v251, s66, 24
	v_writelane_b32 v251, s67, 25
	v_writelane_b32 v251, s68, 26
	v_writelane_b32 v251, s69, 27
	v_writelane_b32 v251, s70, 28
	v_writelane_b32 v251, s71, 29
	v_writelane_b32 v251, s33, 30
	v_writelane_b32 v251, s40, 31
	v_writelane_b32 v251, s41, 32
	v_writelane_b32 v251, s42, 33
	v_writelane_b32 v251, s43, 34
	v_writelane_b32 v251, s89, 35
	v_writelane_b32 v251, vcc_lo, 36
	v_writelane_b32 v251, vcc_hi, 37
	s_nop 1
	v_readlane_b32 s0, v250, 0
	v_readlane_b32 s1, v250, 1
	s_nop 3
	s_sub_u32 s0, s0, 0x90
	s_subb_u32 s1, s1, 0
	s_load_dwordx4 s[40:43], s[0:1], 0x10
	s_lshr_b32 s89, s77, 6
	s_sub_i32 s4, s6, 0x80
	s_lshl_b32 s4, s4, 3
	s_add_i32 s4, s4, s89
	s_add_i32 s4, s4, 0x2920
	s_mov_b32 s33, 0x80
	s_mov_b32 s97, 0x38c0
	s_mov_b32 s96, 1
	s_waitcnt vmcnt(0) lgkmcnt(0)
	s_branch .Lp0_entry
.Lp0ret_1:
	s_waitcnt vmcnt(0) lgkmcnt(0)
	v_readlane_b32 s0, v251, 0
	v_readlane_b32 s1, v251, 1
	v_readlane_b32 s4, v251, 2
	v_readlane_b32 s5, v251, 3
	v_readlane_b32 s26, v251, 4
	v_readlane_b32 s27, v251, 5
	v_readlane_b32 s30, v251, 6
	v_readlane_b32 s31, v251, 7
	v_readlane_b32 s34, v251, 8
	v_readlane_b32 s35, v251, 9
	v_readlane_b32 s52, v251, 10
	v_readlane_b32 s53, v251, 11
	v_readlane_b32 s54, v251, 12
	v_readlane_b32 s55, v251, 13
	v_readlane_b32 s56, v251, 14
	v_readlane_b32 s57, v251, 15
	v_readlane_b32 s58, v251, 16
	v_readlane_b32 s59, v251, 17
	v_readlane_b32 s60, v251, 18
	v_readlane_b32 s61, v251, 19
	v_readlane_b32 s62, v251, 20
	v_readlane_b32 s63, v251, 21
	v_readlane_b32 s64, v251, 22
	v_readlane_b32 s65, v251, 23
	v_readlane_b32 s66, v251, 24
	v_readlane_b32 s67, v251, 25
	v_readlane_b32 s68, v251, 26
	v_readlane_b32 s69, v251, 27
	v_readlane_b32 s70, v251, 28
	v_readlane_b32 s71, v251, 29
	v_readlane_b32 s33, v251, 30
	v_readlane_b32 s40, v251, 31
	v_readlane_b32 s41, v251, 32
	v_readlane_b32 s42, v251, 33
	v_readlane_b32 s43, v251, 34
	v_readlane_b32 s89, v251, 35
	v_readlane_b32 vcc_lo, v251, 36
	v_readlane_b32 vcc_hi, v251, 37
	s_nop 3

.Lp0call_2:
	v_writelane_b32 v251, s0, 0
	v_writelane_b32 v251, s1, 1
	v_writelane_b32 v251, s4, 2
	v_writelane_b32 v251, s5, 3
	v_writelane_b32 v251, s26, 4
	v_writelane_b32 v251, s27, 5
	v_writelane_b32 v251, s30, 6
	v_writelane_b32 v251, s31, 7
	v_writelane_b32 v251, s34, 8
	v_writelane_b32 v251, s35, 9
	v_writelane_b32 v251, s52, 10
	v_writelane_b32 v251, s53, 11
	v_writelane_b32 v251, s54, 12
	v_writelane_b32 v251, s55, 13
	v_writelane_b32 v251, s56, 14
	v_writelane_b32 v251, s57, 15
	v_writelane_b32 v251, s58, 16
	v_writelane_b32 v251, s59, 17
	v_writelane_b32 v251, s60, 18
	v_writelane_b32 v251, s61, 19
	v_writelane_b32 v251, s62, 20
	v_writelane_b32 v251, s63, 21
	v_writelane_b32 v251, s64, 22
	v_writelane_b32 v251, s65, 23
	v_writelane_b32 v251, s66, 24
	v_writelane_b32 v251, s67, 25
	v_writelane_b32 v251, s68, 26
	v_writelane_b32 v251, s69, 27
	v_writelane_b32 v251, s70, 28
	v_writelane_b32 v251, s71, 29
	v_writelane_b32 v251, s33, 30
	v_writelane_b32 v251, s40, 31
	v_writelane_b32 v251, s41, 32
	v_writelane_b32 v251, s42, 33
	v_writelane_b32 v251, s43, 34
	v_writelane_b32 v251, s89, 35
	v_writelane_b32 v251, vcc_lo, 36
	v_writelane_b32 v251, vcc_hi, 37
	s_nop 1
	v_readlane_b32 s0, v250, 0
	v_readlane_b32 s1, v250, 1
	s_nop 3
	s_sub_u32 s0, s0, 0x90
	s_subb_u32 s1, s1, 0
	s_load_dwordx4 s[40:43], s[0:1], 0x10
	s_lshr_b32 s89, s77, 6
	s_sub_i32 s4, s6, 0x80
	s_lshl_b32 s4, s4, 3
	s_add_i32 s4, s4, s89
	s_add_i32 s4, s4, 0x38c0
	s_mov_b32 s33, 0x80
	s_mov_b32 s97, 0x4860
	s_mov_b32 s96, 2
	s_waitcnt vmcnt(0) lgkmcnt(0)
	s_branch .Lp0_entry

.Lp0call_3:
	v_writelane_b32 v251, s0, 0
	v_writelane_b32 v251, s1, 1
	v_writelane_b32 v251, s4, 2
	v_writelane_b32 v251, s5, 3
	v_writelane_b32 v251, s26, 4
	v_writelane_b32 v251, s27, 5
	v_writelane_b32 v251, s30, 6
	v_writelane_b32 v251, s31, 7
	v_writelane_b32 v251, s34, 8
	v_writelane_b32 v251, s35, 9
	v_writelane_b32 v251, s52, 10
	v_writelane_b32 v251, s53, 11
	v_writelane_b32 v251, s54, 12
	v_writelane_b32 v251, s55, 13
	v_writelane_b32 v251, s56, 14
	v_writelane_b32 v251, s57, 15
	v_writelane_b32 v251, s58, 16
	v_writelane_b32 v251, s59, 17
	v_writelane_b32 v251, s60, 18
	v_writelane_b32 v251, s61, 19
	v_writelane_b32 v251, s62, 20
	v_writelane_b32 v251, s63, 21
	v_writelane_b32 v251, s64, 22
	v_writelane_b32 v251, s65, 23
	v_writelane_b32 v251, s66, 24
	v_writelane_b32 v251, s67, 25
	v_writelane_b32 v251, s68, 26
	v_writelane_b32 v251, s69, 27
	v_writelane_b32 v251, s70, 28
	v_writelane_b32 v251, s71, 29
	v_writelane_b32 v251, s33, 30
	v_writelane_b32 v251, s40, 31
	v_writelane_b32 v251, s41, 32
	v_writelane_b32 v251, s42, 33
	v_writelane_b32 v251, s43, 34
	v_writelane_b32 v251, s89, 35
	v_writelane_b32 v251, vcc_lo, 36
	v_writelane_b32 v251, vcc_hi, 37
	s_nop 1
	v_readlane_b32 s0, v250, 0
	v_readlane_b32 s1, v250, 1
	s_nop 3
	s_sub_u32 s0, s0, 0x90
	s_subb_u32 s1, s1, 0
	s_load_dwordx4 s[40:43], s[0:1], 0x10
	s_lshr_b32 s89, s77, 6
	s_sub_i32 s4, s6, 0x80
	s_lshl_b32 s4, s4, 3
	s_add_i32 s4, s4, s89
	s_add_i32 s4, s4, 0x4860
	s_mov_b32 s33, 0x80
	s_mov_b32 s97, 0x5800
	s_mov_b32 s96, 3
	s_waitcnt vmcnt(0) lgkmcnt(0)
	s_branch .Lp0_entry

	.amdhsa_kernel _Z6mk_fwd4Args
		.amdhsa_group_segment_fixed_size 0
		.amdhsa_private_segment_fixed_size 0
		.amdhsa_kernarg_size 400
		.amdhsa_user_sgpr_count 2
		.amdhsa_user_sgpr_dispatch_ptr 0
		.amdhsa_user_sgpr_queue_ptr 0
		.amdhsa_user_sgpr_kernarg_segment_ptr 1
		.amdhsa_user_sgpr_dispatch_id 0
		.amdhsa_user_sgpr_kernarg_preload_length 0
		.amdhsa_user_sgpr_kernarg_preload_offset 0
		.amdhsa_user_sgpr_private_segment_size 0
		.amdhsa_uses_dynamic_stack 0
		.amdhsa_enable_private_segment 0
		.amdhsa_system_sgpr_workgroup_id_x 1
		.amdhsa_system_sgpr_workgroup_id_y 0
		.amdhsa_system_sgpr_workgroup_id_z 0
		.amdhsa_system_sgpr_workgroup_info 0
		.amdhsa_system_vgpr_workitem_id 2
		.amdhsa_next_free_vgpr 252
		.amdhsa_next_free_sgpr 98
		.amdhsa_accum_offset 252
		.amdhsa_reserve_vcc 1
		.amdhsa_float_round_mode_32 0
		.amdhsa_float_round_mode_16_64 0
		.amdhsa_float_denorm_mode_32 3
		.amdhsa_float_denorm_mode_16_64 3
		.amdhsa_dx10_clamp 1
		.amdhsa_ieee_mode 1
		.amdhsa_fp16_overflow 0
		.amdhsa_tg_split 0
		.amdhsa_exception_fp_ieee_invalid_op 0
		.amdhsa_exception_fp_denorm_src 0
		.amdhsa_exception_fp_ieee_div_zero 0
		.amdhsa_exception_fp_ieee_overflow 0
		.amdhsa_exception_fp_ieee_underflow 0
		.amdhsa_exception_fp_ieee_inexact 0
		.amdhsa_exception_int_div_zero 0
	.end_amdhsa_kernel

amdhsa.kernels:
  - .agpr_count:     0
    .args:
      - .offset:         0
        .size:           144
        .value_kind:     by_value
      - .offset:         144
        .size:           4
        .value_kind:     hidden_block_count_x
      - .offset:         148
        .size:           4
        .value_kind:     hidden_block_count_y
      - .offset:         152
        .size:           4
        .value_kind:     hidden_block_count_z
      - .offset:         156
        .size:           2
        .value_kind:     hidden_group_size_x
      - .offset:         158
        .size:           2
        .value_kind:     hidden_group_size_y
      - .offset:         160
        .size:           2
        .value_kind:     hidden_group_size_z
      - .offset:         162
        .size:           2
        .value_kind:     hidden_remainder_x
      - .offset:         164
        .size:           2
        .value_kind:     hidden_remainder_y
      - .offset:         166
        .size:           2
        .value_kind:     hidden_remainder_z
      - .offset:         184
        .size:           8
        .value_kind:     hidden_global_offset_x
      - .offset:         192
        .size:           8
        .value_kind:     hidden_global_offset_y
      - .offset:         200
        .size:           8
        .value_kind:     hidden_global_offset_z
      - .offset:         208
        .size:           2
        .value_kind:     hidden_grid_dims
      - .offset:         232
        .size:           8
        .value_kind:     hidden_multigrid_sync_arg
      - .offset:         264
        .size:           4
        .value_kind:     hidden_dynamic_lds_size
    .group_segment_fixed_size: 0
    .kernarg_segment_align: 8
    .kernarg_segment_size: 400
    .language:       OpenCL C
    .language_version:
      - 2
      - 0
    .max_flat_workgroup_size: 512
    .name:           _Z6mk_fwd4Args
    .private_segment_fixed_size: 0
    .sgpr_count:     104
    .sgpr_spill_count: 3
    .symbol:         _Z6mk_fwd4Args.kd
    .uniform_work_group_size: 1
    .uses_dynamic_stack: false
    .vgpr_count:     252
    .vgpr_spill_count: 0
    .wavefront_size: 64
